# half-tile FFN-down plus packed f32 adds in attention loops split into single adds
# baseline (speedup 1.0000x reference)
.LBB0_571:
	v_mul_f32_e32 v159, 0xbe38aa3b, v146
	v_fmamk_f32 v122, v122, 0x3e38aa3b, v159
	v_fmamk_f32 v130, v130, 0x3e38aa3b, v159
	v_fmamk_f32 v131, v131, 0x3e38aa3b, v159
	v_fmamk_f32 v132, v132, 0x3e38aa3b, v159
	v_fmamk_f32 v133, v133, 0x3e38aa3b, v159
	v_exp_f32_e32 v146, v122
	v_fmamk_f32 v122, v123, 0x3e38aa3b, v159
	v_exp_f32_e32 v130, v130
	v_exp_f32_e32 v131, v131
	v_exp_f32_e32 v132, v132
	v_exp_f32_e32 v133, v133
	v_fmamk_f32 v126, v126, 0x3e38aa3b, v159
	v_fmamk_f32 v127, v127, 0x3e38aa3b, v159
	v_fmamk_f32 v128, v128, 0x3e38aa3b, v159
	v_fmamk_f32 v129, v129, 0x3e38aa3b, v159
	v_exp_f32_e32 v147, v122
	v_fmamk_f32 v122, v124, 0x3e38aa3b, v159
	v_fmamk_f32 v118, v118, 0x3e38aa3b, v159
	v_exp_f32_e32 v126, v126
	v_exp_f32_e32 v127, v127
	v_exp_f32_e32 v128, v128
	v_exp_f32_e32 v129, v129
	v_exp_f32_e32 v160, v122
	v_fmamk_f32 v122, v125, 0x3e38aa3b, v159
	v_exp_f32_e32 v176, v118
	v_fmamk_f32 v118, v119, 0x3e38aa3b, v159
	v_exp_f32_e32 v161, v122
	v_exp_f32_e32 v177, v118
	v_fmamk_f32 v118, v120, 0x3e38aa3b, v159
	v_fmac_f32_e32 v159, 0x3e38aa3b, v121
	v_exp_f32_e32 v178, v118
	v_exp_f32_e32 v179, v159
	v_add_f32_e32 v118, v130, v132
	v_add_f32_e32 v119, v131, v133
	v_add_f32_e32 v120, v126, v128
	v_add_f32_e32 v121, v127, v129
	v_add_f32_e32 v118, 0, v118
	v_add_f32_e32 v119, 0, v119
	v_cvt_pk_bf16_f32 v122, v126, v127
	v_add_f32_e32 v118, v120, v118
	v_add_f32_e32 v119, v121, v119
	v_add_f32_e32 v120, v146, v160
	v_add_f32_e32 v121, v147, v161
	v_cvt_pk_bf16_f32 v123, v128, v129
	v_add_f32_e32 v118, v120, v118
	v_add_f32_e32 v119, v121, v119
	v_add_f32_e32 v120, v176, v178
	v_add_f32_e32 v121, v177, v179
	v_cvt_pk_bf16_f32 v124, v146, v147
	v_add_f32_e32 v118, v120, v118
	v_add_f32_e32 v119, v121, v119
	v_cvt_pk_bf16_f32 v120, v130, v131
	v_add_f32_e32 v118, v118, v119
	v_mov_b32_e32 v119, v118
	v_cvt_pk_bf16_f32 v121, v132, v133
	v_add_f32_e32 v118, v148, v118
	v_add_f32_e32 v119, v149, v119
	v_cvt_pk_bf16_f32 v125, v160, v161
	s_waitcnt lgkmcnt(1)
	v_mfma_f32_16x16x32_bf16 v[42:45], v[98:101], v[120:123], v[42:45]
	v_max_f32_e32 v119, v115, v115
	v_cvt_pk_bf16_f32 v126, v176, v177
	v_cvt_pk_bf16_f32 v127, v178, v179
	v_mfma_f32_16x16x32_bf16 v[46:49], v[94:97], v[120:123], v[46:49]
	v_mfma_f32_16x16x32_bf16 v[38:41], v[90:93], v[120:123], v[38:41]
	v_mfma_f32_16x16x32_bf16 v[34:37], v[86:89], v[120:123], v[34:37]
	v_max_f32_e32 v120, v114, v114
	v_max_f32_e32 v119, v120, v119
	v_max3_f32 v120, v117, v110, v111
	v_max3_f32 v121, v112, v113, v106
	v_max3_f32 v119, v119, v116, v120
	v_max3_f32 v120, v107, v108, v109
	v_max3_f32 v122, v102, v103, v104
	v_max3_f32 v119, v119, v121, v120
	v_mfma_f32_16x16x32_bf16 v[42:45], v[82:85], v[124:127], v[42:45]
	v_max3_f32 v119, v119, v122, v105
	v_sub_f32_e32 v120, v119, v151
	v_mul_f32_e32 v120, 0x3e38aa3b, v120
	v_mfma_f32_16x16x32_bf16 v[46:49], v[78:81], v[124:127], v[46:49]
	v_cmp_lt_f32_e32 vcc, s9, v120
	v_mfma_f32_16x16x32_bf16 v[38:41], v[74:77], v[124:127], v[38:41]
	s_waitcnt lgkmcnt(0)
	v_mfma_f32_16x16x32_bf16 v[34:37], v[70:73], v[124:127], v[34:37]
	s_cbranch_vccz .LBB0_573
	v_mbcnt_hi_u32_b32 v120, -1, v203
	v_and_b32_e32 v122, 64, v120
	v_xor_b32_e32 v121, 16, v120
	v_add_u32_e32 v122, 64, v122
	v_cmp_lt_i32_e32 vcc, v121, v122
	s_nop 1
	v_cndmask_b32_e32 v121, v120, v121, vcc
	v_lshlrev_b32_e32 v121, 2, v121
	ds_bpermute_b32 v121, v121, v119
	v_max_f32_e32 v119, v119, v119
	s_waitcnt lgkmcnt(0)
	v_max_f32_e32 v121, v121, v121
	v_max_f32_e32 v119, v119, v121
	v_xor_b32_e32 v121, 32, v120
	v_cmp_lt_i32_e32 vcc, v121, v122
	s_nop 1
	v_cndmask_b32_e32 v120, v120, v121, vcc
	v_lshlrev_b32_e32 v120, 2, v120
	ds_bpermute_b32 v120, v120, v119
	s_waitcnt lgkmcnt(0)
	v_max3_f32 v119, v151, v119, v120
	v_sub_f32_e32 v120, v151, v119
	v_mul_f32_e32 v120, 0x3e38aa3b, v120
	v_exp_f32_e32 v120, v120
	v_mov_b32_e32 v151, v119
	v_mul_f32_e32 v149, v149, v120
	v_pk_mul_f32 v[20:21], v[20:21], v[120:121] op_sel_hi:[1,0]
	v_pk_mul_f32 v[18:19], v[18:19], v[120:121] op_sel_hi:[1,0]
	v_pk_mul_f32 v[24:25], v[24:25], v[120:121] op_sel_hi:[1,0]
	v_pk_mul_f32 v[22:23], v[22:23], v[120:121] op_sel_hi:[1,0]
	v_pk_mul_f32 v[28:29], v[28:29], v[120:121] op_sel_hi:[1,0]
	v_pk_mul_f32 v[26:27], v[26:27], v[120:121] op_sel_hi:[1,0]
	v_pk_mul_f32 v[32:33], v[32:33], v[120:121] op_sel_hi:[1,0]
	v_pk_mul_f32 v[30:31], v[30:31], v[120:121] op_sel_hi:[1,0]
.LBB0_573:
	v_mul_f32_e32 v125, 0xbe38aa3b, v151
	v_fmamk_f32 v114, v114, 0x3e38aa3b, v125
	v_exp_f32_e32 v120, v114
	v_fmamk_f32 v114, v115, 0x3e38aa3b, v125
	v_exp_f32_e32 v121, v114
	v_fmamk_f32 v114, v116, 0x3e38aa3b, v125
	v_exp_f32_e32 v116, v114
	v_fmamk_f32 v114, v117, 0x3e38aa3b, v125
	v_exp_f32_e32 v117, v114
	v_fmamk_f32 v110, v110, 0x3e38aa3b, v125
	v_fmamk_f32 v111, v111, 0x3e38aa3b, v125
	v_fmamk_f32 v112, v112, 0x3e38aa3b, v125
	v_fmamk_f32 v113, v113, 0x3e38aa3b, v125
	v_fmamk_f32 v102, v102, 0x3e38aa3b, v125
	v_exp_f32_e32 v110, v110
	v_exp_f32_e32 v111, v111
	v_exp_f32_e32 v112, v112
	v_exp_f32_e32 v113, v113
	v_fmamk_f32 v106, v106, 0x3e38aa3b, v125
	v_fmamk_f32 v107, v107, 0x3e38aa3b, v125
	v_fmamk_f32 v108, v108, 0x3e38aa3b, v125
	v_fmamk_f32 v109, v109, 0x3e38aa3b, v125
	v_exp_f32_e32 v122, v102
	v_fmamk_f32 v102, v103, 0x3e38aa3b, v125
	v_exp_f32_e32 v106, v106
	v_exp_f32_e32 v107, v107
	v_exp_f32_e32 v108, v108
	v_exp_f32_e32 v109, v109
	v_exp_f32_e32 v123, v102
	v_fmamk_f32 v102, v104, 0x3e38aa3b, v125
	v_fmac_f32_e32 v125, 0x3e38aa3b, v105
	v_exp_f32_e32 v124, v102
	v_exp_f32_e32 v125, v125
	v_add_f32_e32 v102, v120, v116
	v_add_f32_e32 v103, v121, v117
	v_add_f32_e32 v104, v110, v112
	v_add_f32_e32 v105, v111, v113
	v_add_f32_e32 v102, 0, v102
	v_add_f32_e32 v103, 0, v103
	v_mov_b32_e32 v119, v149
	v_add_f32_e32 v102, v104, v102
	v_add_f32_e32 v103, v105, v103
	v_add_f32_e32 v104, v106, v108
	v_add_f32_e32 v105, v107, v109
	v_cvt_pk_bf16_f32 v106, v106, v107
	v_add_f32_e32 v102, v104, v102
	v_add_f32_e32 v103, v105, v103
	v_add_f32_e32 v104, v122, v124
	v_add_f32_e32 v105, v123, v125
	v_cvt_pk_bf16_f32 v107, v108, v109
	v_add_f32_e32 v102, v104, v102
	v_add_f32_e32 v103, v105, v103
	v_cvt_pk_bf16_f32 v104, v110, v111
	v_add_f32_e32 v102, v102, v103
	v_add_f32_e32 v114, v118, v102
	v_add_f32_e32 v115, v119, v102
	v_cvt_pk_bf16_f32 v102, v120, v121
	v_cvt_pk_bf16_f32 v103, v116, v117
	v_cvt_pk_bf16_f32 v105, v112, v113
	v_cvt_pk_bf16_f32 v108, v122, v123
	v_cvt_pk_bf16_f32 v109, v124, v125
	v_mfma_f32_16x16x32_bf16 v[18:21], v[98:101], v[102:105], v[18:21]
	v_readlane_b32 s20, v254, 19
	v_readlane_b32 s21, v254, 20
	v_mov_b64_e32 v[146:147], v[150:151]
	v_mfma_f32_16x16x32_bf16 v[22:25], v[94:97], v[102:105], v[22:25]
	v_lshl_add_u64 v[140:141], s[20:21], 1, v[140:141]
	s_cmp_lg_u32 s15, s18
	v_mfma_f32_16x16x32_bf16 v[26:29], v[90:93], v[102:105], v[26:29]
	s_barrier
	v_mfma_f32_16x16x32_bf16 v[30:33], v[86:89], v[102:105], v[30:33]
	v_mfma_f32_16x16x32_bf16 v[18:21], v[82:85], v[106:109], v[18:21]
	v_mfma_f32_16x16x32_bf16 v[22:25], v[78:81], v[106:109], v[22:25]
	v_mfma_f32_16x16x32_bf16 v[26:29], v[74:77], v[106:109], v[26:29]
	v_mfma_f32_16x16x32_bf16 v[30:33], v[70:73], v[106:109], v[30:33]
	s_cbranch_scc0 .LBB0_575
	v_mov_b32_e32 v119, v115
	v_mov_b64_e32 v[148:149], v[118:119]
	s_mov_b32 s19, s18
	s_branch .LBB0_562

.LBB0_581:
	v_mul_f32_e32 v0, 0xbe38aa3b, v146
	v_fmamk_f32 v102, v102, 0x3e38aa3b, v0
	v_fmamk_f32 v110, v110, 0x3e38aa3b, v0
	v_fmamk_f32 v111, v111, 0x3e38aa3b, v0
	v_fmamk_f32 v112, v112, 0x3e38aa3b, v0
	v_fmamk_f32 v113, v113, 0x3e38aa3b, v0
	v_exp_f32_e32 v114, v102
	v_fmamk_f32 v102, v103, 0x3e38aa3b, v0
	v_mov_b32_e32 v119, v115
	v_exp_f32_e32 v110, v110
	v_exp_f32_e32 v111, v111
	v_exp_f32_e32 v112, v112
	v_exp_f32_e32 v113, v113
	v_fmamk_f32 v106, v106, 0x3e38aa3b, v0
	v_fmamk_f32 v107, v107, 0x3e38aa3b, v0
	v_fmamk_f32 v108, v108, 0x3e38aa3b, v0
	v_fmamk_f32 v109, v109, 0x3e38aa3b, v0
	v_exp_f32_e32 v115, v102
	v_fmamk_f32 v102, v104, 0x3e38aa3b, v0
	v_fmamk_f32 v98, v98, 0x3e38aa3b, v0
	v_exp_f32_e32 v106, v106
	v_exp_f32_e32 v107, v107
	v_exp_f32_e32 v108, v108
	v_exp_f32_e32 v109, v109
	v_exp_f32_e32 v120, v102
	v_fmamk_f32 v102, v105, 0x3e38aa3b, v0
	v_exp_f32_e32 v122, v98
	v_fmamk_f32 v98, v99, 0x3e38aa3b, v0
	v_exp_f32_e32 v121, v102
	v_exp_f32_e32 v123, v98
	v_fmamk_f32 v98, v100, 0x3e38aa3b, v0
	v_fmac_f32_e32 v0, 0x3e38aa3b, v101
	v_exp_f32_e32 v124, v98
	v_exp_f32_e32 v125, v0
	v_add_f32_e32 v98, v110, v112
	v_add_f32_e32 v99, v111, v113
	v_add_f32_e32 v100, v106, v108
	v_add_f32_e32 v101, v107, v109
	v_add_f32_e32 v98, 0, v98
	v_add_f32_e32 v99, 0, v99
	v_cvt_pk_bf16_f32 v104, v114, v115
	v_add_f32_e32 v98, v100, v98
	v_add_f32_e32 v99, v101, v99
	v_add_f32_e32 v100, v114, v120
	v_add_f32_e32 v101, v115, v121
	v_cvt_pk_bf16_f32 v105, v120, v121
	v_add_f32_e32 v98, v100, v98
	v_add_f32_e32 v99, v101, v99
	v_add_f32_e32 v100, v122, v124
	v_add_f32_e32 v101, v123, v125
	v_max_f32_e32 v0, v95, v95
	v_add_f32_e32 v98, v100, v98
	v_add_f32_e32 v99, v101, v99
	v_cvt_pk_bf16_f32 v100, v106, v107
	v_add_f32_e32 v98, v98, v99
	v_mov_b32_e32 v99, v98
	v_cvt_pk_bf16_f32 v101, v108, v109
	v_add_f32_e32 v102, v118, v98
	v_add_f32_e32 v103, v119, v99
	v_cvt_pk_bf16_f32 v98, v110, v111
	v_cvt_pk_bf16_f32 v99, v112, v113
	v_cvt_pk_bf16_f32 v106, v122, v123
	v_cvt_pk_bf16_f32 v107, v124, v125
	s_waitcnt lgkmcnt(3)
	v_mfma_f32_16x16x32_bf16 v[42:45], v[58:61], v[98:101], v[42:45]
	s_waitcnt lgkmcnt(1)
	v_mfma_f32_16x16x32_bf16 v[46:49], v[62:65], v[98:101], v[46:49]
	v_mfma_f32_16x16x32_bf16 v[108:111], v[66:69], v[98:101], v[38:41]
	v_mfma_f32_16x16x32_bf16 v[98:101], v[74:77], v[98:101], v[34:37]
	v_mfma_f32_16x16x32_bf16 v[38:41], v[82:85], v[104:107], v[46:49]
	v_mfma_f32_16x16x32_bf16 v[46:49], v[90:93], v[104:107], v[98:101]
	s_nop 5
	v_max_f32_e32 v98, v94, v94
	v_max_f32_e32 v0, v98, v0
	v_max3_f32 v98, v97, v70, v71
	v_max3_f32 v99, v72, v73, v54
	v_max3_f32 v0, v0, v96, v98
	v_max3_f32 v98, v55, v56, v57
	v_max3_f32 v100, v50, v51, v52
	v_max3_f32 v0, v0, v99, v98
	s_waitcnt lgkmcnt(0)
	v_mfma_f32_16x16x32_bf16 v[34:37], v[78:81], v[104:107], v[42:45]
	v_max3_f32 v0, v0, v100, v53
	v_sub_f32_e32 v98, v0, v117
	v_mul_f32_e32 v98, 0x3e38aa3b, v98
	v_mfma_f32_16x16x32_bf16 v[42:45], v[86:89], v[104:107], v[108:111]
	v_cmp_lt_f32_e32 vcc, s4, v98
	s_cbranch_vccz .LBB0_583
	v_mbcnt_hi_u32_b32 v98, -1, v203
	v_and_b32_e32 v100, 64, v98
	v_xor_b32_e32 v99, 16, v98
	v_add_u32_e32 v100, 64, v100
	v_cmp_lt_i32_e32 vcc, v99, v100
	s_nop 1
	v_cndmask_b32_e32 v99, v98, v99, vcc
	v_lshlrev_b32_e32 v99, 2, v99
	ds_bpermute_b32 v99, v99, v0
	v_max_f32_e32 v0, v0, v0
	s_waitcnt lgkmcnt(0)
	v_max_f32_e32 v99, v99, v99
	v_max_f32_e32 v0, v0, v99
	v_xor_b32_e32 v99, 32, v98
	v_cmp_lt_i32_e32 vcc, v99, v100
	s_nop 1
	v_cndmask_b32_e32 v98, v98, v99, vcc
	v_lshlrev_b32_e32 v98, 2, v98
	ds_bpermute_b32 v98, v98, v0
	s_waitcnt lgkmcnt(0)
	v_max3_f32 v100, v117, v0, v98
	v_sub_f32_e32 v0, v117, v100
	v_mul_f32_e32 v0, 0x3e38aa3b, v0
	v_exp_f32_e32 v0, v0
	v_mov_b32_e32 v117, v100
	v_mul_f32_e32 v119, v119, v0
	v_pk_mul_f32 v[20:21], v[20:21], v[0:1] op_sel_hi:[1,0]
	v_pk_mul_f32 v[18:19], v[18:19], v[0:1] op_sel_hi:[1,0]
	v_pk_mul_f32 v[24:25], v[24:25], v[0:1] op_sel_hi:[1,0]
	v_pk_mul_f32 v[22:23], v[22:23], v[0:1] op_sel_hi:[1,0]
	v_pk_mul_f32 v[28:29], v[28:29], v[0:1] op_sel_hi:[1,0]
	v_pk_mul_f32 v[26:27], v[26:27], v[0:1] op_sel_hi:[1,0]
	v_pk_mul_f32 v[32:33], v[32:33], v[0:1] op_sel_hi:[1,0]
	v_pk_mul_f32 v[30:31], v[30:31], v[0:1] op_sel_hi:[1,0]
.LBB0_583:
	v_mul_f32_e32 v0, 0xbe38aa3b, v117
	v_fmamk_f32 v94, v94, 0x3e38aa3b, v0
	v_fmamk_f32 v95, v95, 0x3e38aa3b, v0
	v_fmamk_f32 v96, v96, 0x3e38aa3b, v0
	v_fmamk_f32 v97, v97, 0x3e38aa3b, v0
	v_exp_f32_e32 v94, v94
	v_exp_f32_e32 v95, v95
	v_exp_f32_e32 v96, v96
	v_exp_f32_e32 v97, v97
	v_fmamk_f32 v70, v70, 0x3e38aa3b, v0
	v_fmamk_f32 v71, v71, 0x3e38aa3b, v0
	v_fmamk_f32 v72, v72, 0x3e38aa3b, v0
	v_fmamk_f32 v73, v73, 0x3e38aa3b, v0
	v_fmamk_f32 v54, v54, 0x3e38aa3b, v0
	v_fmamk_f32 v55, v55, 0x3e38aa3b, v0
	v_fmamk_f32 v56, v56, 0x3e38aa3b, v0
	v_fmamk_f32 v57, v57, 0x3e38aa3b, v0
	v_fmamk_f32 v50, v50, 0x3e38aa3b, v0
	v_exp_f32_e32 v70, v70
	v_exp_f32_e32 v71, v71
	v_exp_f32_e32 v72, v72
	v_exp_f32_e32 v73, v73
	v_exp_f32_e32 v54, v54
	v_exp_f32_e32 v55, v55
	v_exp_f32_e32 v56, v56
	v_exp_f32_e32 v57, v57
	v_exp_f32_e32 v104, v50
	v_fmamk_f32 v50, v51, 0x3e38aa3b, v0
	v_exp_f32_e32 v105, v50
	v_fmamk_f32 v50, v52, 0x3e38aa3b, v0
	v_fmac_f32_e32 v0, 0x3e38aa3b, v53
	v_exp_f32_e32 v106, v50
	v_exp_f32_e32 v107, v0
	v_add_f32_e32 v50, v94, v96
	v_add_f32_e32 v51, v95, v97
	v_add_f32_e32 v52, v70, v72
	v_add_f32_e32 v53, v71, v73
	v_add_f32_e32 v50, 0, v50
	v_add_f32_e32 v51, 0, v51
	s_nop 0
	v_add_f32_e32 v50, v52, v50
	v_add_f32_e32 v51, v53, v51
	v_add_f32_e32 v52, v54, v56
	v_add_f32_e32 v53, v55, v57
	s_barrier
	v_add_f32_e32 v50, v52, v50
	v_add_f32_e32 v51, v53, v51
	v_add_f32_e32 v52, v104, v106
	v_add_f32_e32 v53, v105, v107
	s_nop 0
	v_add_f32_e32 v50, v52, v50
	v_add_f32_e32 v51, v53, v51
	v_cvt_pk_bf16_f32 v52, v70, v71
	v_add_f32_e32 v0, v50, v51
	v_cvt_pk_bf16_f32 v50, v94, v95
	v_cvt_pk_bf16_f32 v51, v96, v97
	v_cvt_pk_bf16_f32 v53, v72, v73
	ds_read_b128 v[70:73], v153 offset:2304
	v_cvt_pk_bf16_f32 v54, v54, v55
	v_mfma_f32_16x16x32_bf16 v[18:21], v[58:61], v[50:53], v[18:21]
	v_cvt_pk_bf16_f32 v55, v56, v57
	v_cvt_pk_bf16_f32 v56, v104, v105
	v_cvt_pk_bf16_f32 v57, v106, v107
	v_mfma_f32_16x16x32_bf16 v[22:25], v[62:65], v[50:53], v[22:25]
	ds_read_b128 v[62:65], v153 offset:4672
	ds_read_b128 v[58:61], v153 offset:6976
	v_mov_b32_e32 v103, v119
	v_mfma_f32_16x16x32_bf16 v[26:29], v[66:69], v[50:53], v[26:29]
	ds_read_b128 v[66:69], v153
	v_add_f32_e32 v100, v102, v0
	v_add_f32_e32 v101, v103, v0
	v_mov_b64_e32 v[98:99], v[116:117]
	v_mfma_f32_16x16x32_bf16 v[30:33], v[74:77], v[50:53], v[30:33]
	ds_read_b128 v[74:77], v153 offset:64
	ds_read_b128 v[50:53], v153 offset:6912
	v_mfma_f32_16x16x32_bf16 v[18:21], v[78:81], v[54:57], v[18:21]
	ds_read_b128 v[78:81], v153 offset:2368
	v_mfma_f32_16x16x32_bf16 v[22:25], v[82:85], v[54:57], v[22:25]
	v_mfma_f32_16x16x32_bf16 v[26:29], v[86:89], v[54:57], v[26:29]
	v_mfma_f32_16x16x32_bf16 v[30:33], v[90:93], v[54:57], v[30:33]
	ds_read_b128 v[54:57], v153 offset:4608
	s_waitcnt lgkmcnt(4)
	v_mfma_f32_16x16x32_bf16 v[82:85], v[66:69], v[14:17], 0
	s_waitcnt lgkmcnt(3)
	v_mfma_f32_16x16x32_bf16 v[82:85], v[74:77], v[10:13], v[82:85]
	v_mfma_f32_16x16x32_bf16 v[86:89], v[70:73], v[14:17], 0
	s_waitcnt lgkmcnt(1)
	v_mfma_f32_16x16x32_bf16 v[86:89], v[78:81], v[10:13], v[86:89]
	s_nop 4
	v_max_f32_e32 v0, v83, v83
	v_max_f32_e32 v100, v82, v82
	v_max_f32_e32 v0, v100, v0
	s_waitcnt lgkmcnt(0)
	v_mfma_f32_16x16x32_bf16 v[90:93], v[54:57], v[14:17], 0
	v_mfma_f32_16x16x32_bf16 v[90:93], v[62:65], v[10:13], v[90:93]
	v_max3_f32 v100, v85, v86, v87
	v_max3_f32 v0, v0, v84, v100
	v_mfma_f32_16x16x32_bf16 v[14:17], v[50:53], v[14:17], 0
	v_mfma_f32_16x16x32_bf16 v[94:97], v[58:61], v[10:13], v[14:17]
	s_nop 3
	v_max3_f32 v103, v88, v89, v90
	v_max3_f32 v100, v91, v92, v93
	v_max3_f32 v0, v0, v103, v100
	v_mfma_f32_16x16x32_bf16 v[10:13], v[66:69], v[2:5], 0
	ds_read_b128 v[14:17], v153 offset:9280
	v_max3_f32 v104, v94, v95, v96
	v_max3_f32 v0, v0, v104, v97
	v_mfma_f32_16x16x32_bf16 v[66:69], v[74:77], v[6:9], v[10:13]
	v_sub_f32_e32 v100, v0, v98
	v_mul_f32_e32 v100, 0x3e38aa3b, v100
	v_cmp_lt_f32_e32 vcc, s4, v100
	v_mfma_f32_16x16x32_bf16 v[10:13], v[70:73], v[2:5], 0
	v_mfma_f32_16x16x32_bf16 v[70:73], v[78:81], v[6:9], v[10:13]
	v_mfma_f32_16x16x32_bf16 v[10:13], v[54:57], v[2:5], 0
	ds_read_b128 v[54:57], v153 offset:13824
	v_mfma_f32_16x16x32_bf16 v[78:81], v[62:65], v[6:9], v[10:13]
	ds_read_b128 v[62:65], v153 offset:9216
	v_mfma_f32_16x16x32_bf16 v[2:5], v[50:53], v[2:5], 0
	ds_read_b128 v[50:53], v153 offset:16128
	s_nop 2
	ds_read_b128 v[10:13], v153 offset:16192
	v_mfma_f32_16x16x32_bf16 v[74:77], v[58:61], v[6:9], v[2:5]
	ds_read_b128 v[58:61], v153 offset:11520
	ds_read_b128 v[6:9], v153 offset:13888
	s_nop 0
	ds_read_b128 v[2:5], v153 offset:11584
	s_cbranch_vccz .LBB0_585
	v_mbcnt_hi_u32_b32 v100, -1, v203
	v_and_b32_e32 v104, 64, v100
	v_xor_b32_e32 v103, 16, v100
	v_add_u32_e32 v104, 64, v104
	v_cmp_lt_i32_e32 vcc, v103, v104
	s_nop 1
	v_cndmask_b32_e32 v103, v100, v103, vcc
	v_lshlrev_b32_e32 v103, 2, v103
	ds_bpermute_b32 v103, v103, v0
	v_max_f32_e32 v0, v0, v0
	s_waitcnt lgkmcnt(0)
	v_max_f32_e32 v103, v103, v103
	v_max_f32_e32 v0, v0, v103
	v_xor_b32_e32 v103, 32, v100
	v_cmp_lt_i32_e32 vcc, v103, v104
	s_nop 1
	v_cndmask_b32_e32 v100, v100, v103, vcc
	v_lshlrev_b32_e32 v100, 2, v100
	ds_bpermute_b32 v100, v100, v0
	s_waitcnt lgkmcnt(0)
	v_max3_f32 v103, v98, v0, v100
	v_sub_f32_e32 v0, v98, v103
	v_mul_f32_e32 v0, 0x3e38aa3b, v0
	v_exp_f32_e32 v0, v0
	v_mov_b32_e32 v98, v103
	v_mul_f32_e32 v100, v102, v0
	v_pk_mul_f32 v[36:37], v[36:37], v[0:1] op_sel_hi:[1,0]
	v_pk_mul_f32 v[34:35], v[34:35], v[0:1] op_sel_hi:[1,0]
	v_pk_mul_f32 v[40:41], v[40:41], v[0:1] op_sel_hi:[1,0]
	v_pk_mul_f32 v[38:39], v[38:39], v[0:1] op_sel_hi:[1,0]
	v_pk_mul_f32 v[44:45], v[44:45], v[0:1] op_sel_hi:[1,0]
	v_pk_mul_f32 v[42:43], v[42:43], v[0:1] op_sel_hi:[1,0]
	v_pk_mul_f32 v[48:49], v[48:49], v[0:1] op_sel_hi:[1,0]
	v_pk_mul_f32 v[46:47], v[46:47], v[0:1] op_sel_hi:[1,0]
	s_branch .LBB0_586

.LBB0_586:
	v_mul_f32_e32 v0, 0xbe38aa3b, v98
	v_fmamk_f32 v82, v82, 0x3e38aa3b, v0
	v_fmamk_f32 v83, v83, 0x3e38aa3b, v0
	v_fmamk_f32 v84, v84, 0x3e38aa3b, v0
	v_fmamk_f32 v85, v85, 0x3e38aa3b, v0
	v_fmamk_f32 v86, v86, 0x3e38aa3b, v0
	v_fmamk_f32 v87, v87, 0x3e38aa3b, v0
	v_fmamk_f32 v88, v88, 0x3e38aa3b, v0
	v_fmamk_f32 v89, v89, 0x3e38aa3b, v0
	v_exp_f32_e32 v82, v82
	v_exp_f32_e32 v83, v83
	v_exp_f32_e32 v84, v84
	v_exp_f32_e32 v85, v85
	v_exp_f32_e32 v86, v86
	v_exp_f32_e32 v87, v87
	v_exp_f32_e32 v88, v88
	v_exp_f32_e32 v89, v89
	v_fmamk_f32 v90, v90, 0x3e38aa3b, v0
	v_fmamk_f32 v91, v91, 0x3e38aa3b, v0
	v_fmamk_f32 v92, v92, 0x3e38aa3b, v0
	v_fmamk_f32 v93, v93, 0x3e38aa3b, v0
	v_fmamk_f32 v94, v94, 0x3e38aa3b, v0
	v_fmamk_f32 v95, v95, 0x3e38aa3b, v0
	v_fmamk_f32 v96, v96, 0x3e38aa3b, v0
	v_fmac_f32_e32 v0, 0x3e38aa3b, v97
	v_exp_f32_e32 v90, v90
	v_exp_f32_e32 v91, v91
	v_exp_f32_e32 v92, v92
	v_exp_f32_e32 v93, v93
	v_exp_f32_e32 v94, v94
	v_exp_f32_e32 v95, v95
	v_exp_f32_e32 v96, v96
	v_exp_f32_e32 v97, v0
	v_add_f32_e32 v102, v82, v84
	v_add_f32_e32 v103, v83, v85
	v_cvt_pk_bf16_f32 v82, v82, v83
	v_cvt_pk_bf16_f32 v83, v84, v85
	v_cvt_pk_bf16_f32 v84, v86, v87
	v_cvt_pk_bf16_f32 v85, v88, v89
	v_max_f32_e32 v0, v67, v67
	v_add_f32_e32 v102, 0, v102
	v_add_f32_e32 v103, 0, v103
	s_waitcnt lgkmcnt(5)
	v_mfma_f32_16x16x32_bf16 v[34:37], v[62:65], v[82:85], v[34:37]
	v_add_f32_e64 v104, v86, v88
	v_add_f32_e64 v105, v87, v89
	v_cvt_pk_bf16_f32 v86, v90, v91
	v_add_f32_e32 v102, v104, v102
	v_add_f32_e32 v103, v105, v103
	s_waitcnt lgkmcnt(2)
	v_mfma_f32_16x16x32_bf16 v[38:41], v[58:61], v[82:85], v[38:41]
	v_add_f32_e64 v104, v90, v92
	v_add_f32_e64 v105, v91, v93
	v_cvt_pk_bf16_f32 v87, v92, v93
	v_cvt_pk_bf16_f32 v88, v94, v95
	v_mfma_f32_16x16x32_bf16 v[42:45], v[54:57], v[82:85], v[42:45]
	v_cvt_pk_bf16_f32 v89, v96, v97
	v_add_f32_e32 v102, v104, v102
	v_add_f32_e32 v103, v105, v103
	v_add_f32_e32 v104, v94, v96
	v_add_f32_e32 v105, v95, v97
	v_mfma_f32_16x16x32_bf16 v[46:49], v[50:53], v[82:85], v[46:49]
	v_max_f32_e32 v82, v66, v66
	v_max_f32_e32 v0, v82, v0
	v_max3_f32 v82, v69, v70, v71
	v_max3_f32 v83, v72, v73, v78
	v_max3_f32 v0, v0, v68, v82
	v_max3_f32 v82, v79, v80, v81
	v_max3_f32 v84, v74, v75, v76
	v_max3_f32 v0, v0, v83, v82
	v_mfma_f32_16x16x32_bf16 v[34:37], v[14:17], v[86:89], v[34:37]
	v_max3_f32 v82, v0, v84, v77
	v_add_f32_e32 v102, v104, v102
	v_add_f32_e32 v103, v105, v103
	v_sub_f32_e32 v0, v82, v99
	s_waitcnt lgkmcnt(0)
	v_mfma_f32_16x16x32_bf16 v[38:41], v[2:5], v[86:89], v[38:41]
	v_add_f32_e32 v102, v102, v103
	v_mov_b32_e32 v103, v102
	v_mul_f32_e32 v0, 0x3e38aa3b, v0
	v_add_f32_e32 v102, v100, v102
	v_add_f32_e32 v103, v101, v103
	v_mfma_f32_16x16x32_bf16 v[42:45], v[6:9], v[86:89], v[42:45]
	v_cmp_lt_f32_e32 vcc, s4, v0
	v_mfma_f32_16x16x32_bf16 v[46:49], v[10:13], v[86:89], v[46:49]
	s_cbranch_vccz .LBB0_634
	v_mbcnt_hi_u32_b32 v0, -1, v203
	v_and_b32_e32 v83, 64, v0
	v_xor_b32_e32 v98, 16, v0
	v_add_u32_e32 v100, 64, v83
	v_cmp_lt_i32_e32 vcc, v98, v100
	v_xor_b32_e32 v103, 32, v0
	s_nop 0
	v_cndmask_b32_e32 v83, v0, v98, vcc
	v_lshlrev_b32_e32 v83, 2, v83
	ds_bpermute_b32 v83, v83, v82
	v_max_f32_e32 v82, v82, v82
	v_cmp_lt_i32_e32 vcc, v103, v100
	s_waitcnt lgkmcnt(0)
	v_max_f32_e32 v83, v83, v83
	v_max_f32_e32 v82, v82, v83
	v_cndmask_b32_e32 v83, v0, v103, vcc
	v_lshlrev_b32_e32 v83, 2, v83
	ds_bpermute_b32 v83, v83, v82
	s_waitcnt lgkmcnt(0)
	v_max3_f32 v105, v99, v82, v83
	v_sub_f32_e32 v82, v99, v105
	v_mul_f32_e32 v82, 0x3e38aa3b, v82
	v_exp_f32_e32 v82, v82
	s_nop 0
	v_mul_f32_e32 v104, v101, v82
	v_pk_mul_f32 v[96:97], v[20:21], v[82:83] op_sel_hi:[1,0]
	v_pk_mul_f32 v[94:95], v[18:19], v[82:83] op_sel_hi:[1,0]
	v_pk_mul_f32 v[92:93], v[24:25], v[82:83] op_sel_hi:[1,0]
	v_pk_mul_f32 v[90:91], v[22:23], v[82:83] op_sel_hi:[1,0]
	v_pk_mul_f32 v[88:89], v[28:29], v[82:83] op_sel_hi:[1,0]
	v_pk_mul_f32 v[86:87], v[26:27], v[82:83] op_sel_hi:[1,0]
	v_pk_mul_f32 v[84:85], v[32:33], v[82:83] op_sel_hi:[1,0]
	v_pk_mul_f32 v[82:83], v[30:31], v[82:83] op_sel_hi:[1,0]
	s_cbranch_execnz .LBB0_589

.LBB0_589:
	v_mul_f32_e32 v33, 0xbe38aa3b, v105
	v_fmamk_f32 v18, v66, 0x3e38aa3b, v33
	v_fmamk_f32 v19, v67, 0x3e38aa3b, v33
	v_fmamk_f32 v20, v68, 0x3e38aa3b, v33
	v_fmamk_f32 v21, v69, 0x3e38aa3b, v33
	v_exp_f32_e32 v18, v18
	v_exp_f32_e32 v19, v19
	v_exp_f32_e32 v20, v20
	v_exp_f32_e32 v21, v21
	v_fmamk_f32 v22, v70, 0x3e38aa3b, v33
	v_fmamk_f32 v23, v71, 0x3e38aa3b, v33
	v_fmamk_f32 v24, v72, 0x3e38aa3b, v33
	v_fmamk_f32 v25, v73, 0x3e38aa3b, v33
	v_exp_f32_e32 v22, v22
	v_exp_f32_e32 v23, v23
	v_exp_f32_e32 v24, v24
	v_exp_f32_e32 v25, v25
	v_fmamk_f32 v26, v78, 0x3e38aa3b, v33
	v_fmamk_f32 v27, v79, 0x3e38aa3b, v33
	v_fmamk_f32 v28, v80, 0x3e38aa3b, v33
	v_fmamk_f32 v29, v81, 0x3e38aa3b, v33
	v_exp_f32_e32 v26, v26
	v_exp_f32_e32 v27, v27
	v_exp_f32_e32 v28, v28
	v_exp_f32_e32 v29, v29
	v_fmamk_f32 v30, v74, 0x3e38aa3b, v33
	v_fmamk_f32 v31, v75, 0x3e38aa3b, v33
	v_fmamk_f32 v32, v76, 0x3e38aa3b, v33
	v_fmac_f32_e32 v33, 0x3e38aa3b, v77
	v_exp_f32_e32 v30, v30
	v_exp_f32_e32 v31, v31
	v_exp_f32_e32 v32, v32
	v_exp_f32_e32 v33, v33
	v_add_f32_e32 v66, v18, v20
	v_add_f32_e32 v67, v19, v21
	v_add_f32_e32 v68, v22, v24
	v_add_f32_e32 v69, v23, v25
	v_add_f32_e32 v66, 0, v66
	v_add_f32_e32 v67, 0, v67
	v_cvt_pk_bf16_f32 v18, v18, v19
	v_add_f32_e32 v66, v68, v66
	v_add_f32_e32 v67, v69, v67
	v_add_f32_e32 v68, v26, v28
	v_add_f32_e32 v69, v27, v29
	v_cvt_pk_bf16_f32 v19, v20, v21
	v_cvt_pk_bf16_f32 v20, v22, v23
	v_cvt_pk_bf16_f32 v21, v24, v25
	v_add_f32_e32 v66, v68, v66
	v_add_f32_e32 v67, v69, v67
	v_add_f32_e32 v68, v30, v32
	v_add_f32_e32 v69, v31, v33
	v_cvt_pk_bf16_f32 v24, v30, v31
	v_cvt_pk_bf16_f32 v25, v32, v33
	v_mfma_f32_16x16x32_bf16 v[30:33], v[58:61], v[18:21], v[90:93]
	v_cvt_pk_bf16_f32 v22, v26, v27
	v_cvt_pk_bf16_f32 v23, v28, v29
	v_cmp_lt_i32_e32 vcc, v98, v100
	v_mfma_f32_16x16x32_bf16 v[50:53], v[50:53], v[18:21], v[82:85]
	s_lshl_b64 s[4:5], s[10:11], 11
	v_readlane_b32 s8, v254, 33
	v_readlane_b32 s9, v254, 34
	v_mfma_f32_16x16x32_bf16 v[26:29], v[62:65], v[18:21], v[94:97]
	s_add_u32 s4, s8, s4
	s_addc_u32 s5, s9, s5
	s_lshl_b32 s7, s7, 1
	v_mfma_f32_16x16x32_bf16 v[54:57], v[54:57], v[18:21], v[86:89]
	s_add_u32 s4, s4, s7
	s_addc_u32 s5, s5, 0
	v_mfma_f32_16x16x32_bf16 v[18:21], v[2:5], v[22:25], v[30:33]
	s_barrier
	v_add_f32_e32 v66, v68, v66
	v_add_f32_e32 v67, v69, v67
	v_mfma_f32_16x16x32_bf16 v[2:5], v[10:13], v[22:25], v[50:53]
	v_cndmask_b32_e32 v10, v0, v98, vcc
	v_cmp_lt_i32_e32 vcc, v103, v100
	v_add_f32_e32 v66, v66, v67
	v_mfma_f32_16x16x32_bf16 v[14:17], v[14:17], v[22:25], v[26:29]
	v_cndmask_b32_e32 v0, v0, v103, vcc
	v_add_f32_e32 v66, v104, v66
	s_nop 0
	v_lshlrev_b32_e32 v26, 2, v10
	v_lshlrev_b32_e32 v27, 2, v0
	ds_bpermute_b32 v0, v26, v102
	v_mfma_f32_16x16x32_bf16 v[6:9], v[6:9], v[22:25], v[54:57]
	s_waitcnt lgkmcnt(0)
	v_add_f32_e32 v0, v102, v0
	ds_bpermute_b32 v10, v27, v0
	s_waitcnt lgkmcnt(0)
	v_add_f32_e32 v0, v0, v10
	v_div_scale_f32 v10, s[8:9], v0, v0, 1.0
	v_rcp_f32_e32 v11, v10
	s_nop 0
	v_fma_f32 v12, -v10, v11, 1.0
	v_fmac_f32_e32 v11, v12, v11
	v_div_scale_f32 v12, vcc, 1.0, v0, 1.0
	v_mul_f32_e32 v13, v12, v11
	v_fma_f32 v22, -v10, v13, v12
	v_fmac_f32_e32 v13, v22, v11
	v_fma_f32 v10, -v10, v13, v12
	v_div_fmas_f32 v10, v10, v11, v13
	v_div_fixup_f32 v10, v10, v0, 1.0
	v_lshlrev_b64 v[12:13], 11, v[136:137]
	v_lshl_add_u64 v[12:13], s[4:5], 0, v[12:13]
	v_lshlrev_b32_e32 v0, 3, v152
	v_pk_mul_f32 v[22:23], v[36:37], v[10:11] op_sel_hi:[1,0]
	v_pk_mul_f32 v[24:25], v[34:35], v[10:11] op_sel_hi:[1,0]
	v_lshl_add_u64 v[12:13], v[12:13], 0, v[0:1]
	v_cvt_pk_bf16_f32 v24, v24, v25
	v_cvt_pk_bf16_f32 v25, v22, v23
	global_store_dwordx2 v[12:13], v[24:25], off offset:1536
	v_pk_mul_f32 v[22:23], v[40:41], v[10:11] op_sel_hi:[1,0]
	v_pk_mul_f32 v[24:25], v[38:39], v[10:11] op_sel_hi:[1,0]
	s_nop 0
	v_cvt_pk_bf16_f32 v24, v24, v25
	v_cvt_pk_bf16_f32 v25, v22, v23
	global_store_dwordx2 v[12:13], v[24:25], off offset:1568
	v_pk_mul_f32 v[22:23], v[44:45], v[10:11] op_sel_hi:[1,0]
	v_pk_mul_f32 v[24:25], v[42:43], v[10:11] op_sel_hi:[1,0]
	s_nop 0
	v_cvt_pk_bf16_f32 v24, v24, v25
	v_cvt_pk_bf16_f32 v25, v22, v23
	v_pk_mul_f32 v[22:23], v[48:49], v[10:11] op_sel_hi:[1,0]
	v_pk_mul_f32 v[10:11], v[46:47], v[10:11] op_sel_hi:[1,0]
	global_store_dwordx2 v[12:13], v[24:25], off offset:1600
	v_cvt_pk_bf16_f32 v10, v10, v11
	v_cvt_pk_bf16_f32 v11, v22, v23
	global_store_dwordx2 v[12:13], v[10:11], off offset:1632
	ds_bpermute_b32 v10, v26, v66
	s_waitcnt lgkmcnt(0)
	v_add_f32_e32 v10, v66, v10
	ds_bpermute_b32 v11, v27, v10
	s_waitcnt lgkmcnt(0)
	v_add_f32_e32 v10, v10, v11
	v_div_scale_f32 v11, s[8:9], v10, v10, 1.0
	v_rcp_f32_e32 v12, v11
	s_nop 0
	v_fma_f32 v13, -v11, v12, 1.0
	v_fmac_f32_e32 v12, v13, v12
	v_div_scale_f32 v13, vcc, 1.0, v10, 1.0
	v_mul_f32_e32 v22, v13, v12
	v_fma_f32 v23, -v11, v22, v13
	v_fmac_f32_e32 v22, v23, v12
	v_fma_f32 v11, -v11, v22, v13
	v_div_fmas_f32 v11, v11, v12, v22
	v_div_fixup_f32 v10, v11, v10, 1.0
	v_lshlrev_b64 v[12:13], 11, v[134:135]
	v_lshl_add_u64 v[12:13], s[4:5], 0, v[12:13]
	v_pk_mul_f32 v[16:17], v[16:17], v[10:11] op_sel_hi:[1,0]
	v_pk_mul_f32 v[14:15], v[14:15], v[10:11] op_sel_hi:[1,0]
	v_lshl_add_u64 v[12:13], v[12:13], 0, v[0:1]
	v_cvt_pk_bf16_f32 v14, v14, v15
	v_cvt_pk_bf16_f32 v15, v16, v17
	global_store_dwordx2 v[12:13], v[14:15], off offset:1536
	v_pk_mul_f32 v[14:15], v[20:21], v[10:11] op_sel_hi:[1,0]
	v_pk_mul_f32 v[16:17], v[18:19], v[10:11] op_sel_hi:[1,0]
	v_pk_mul_f32 v[8:9], v[8:9], v[10:11] op_sel_hi:[1,0]
	v_pk_mul_f32 v[6:7], v[6:7], v[10:11] op_sel_hi:[1,0]
	v_pk_mul_f32 v[4:5], v[4:5], v[10:11] op_sel_hi:[1,0]
	v_pk_mul_f32 v[2:3], v[2:3], v[10:11] op_sel_hi:[1,0]
	v_cvt_pk_bf16_f32 v16, v16, v17
	v_cvt_pk_bf16_f32 v17, v14, v15
	v_cvt_pk_bf16_f32 v6, v6, v7
	v_cvt_pk_bf16_f32 v7, v8, v9
	v_cvt_pk_bf16_f32 v2, v2, v3
	v_cvt_pk_bf16_f32 v3, v4, v5
	global_store_dwordx2 v[12:13], v[16:17], off offset:1568
	global_store_dwordx2 v[12:13], v[6:7], off offset:1600
	global_store_dwordx2 v[12:13], v[2:3], off offset:1632
	s_branch .LBB0_645

.LBB0_624:
	v_mul_f32_e32 v153, 0xbe16c740, v160
	v_fmamk_f32 v130, v130, 0x3e16c740, v153
	v_exp_f32_e32 v160, v130
	v_fmamk_f32 v130, v131, 0x3e16c740, v153
	v_exp_f32_e32 v161, v130
	v_fmamk_f32 v130, v132, 0x3e16c740, v153
	v_exp_f32_e32 v196, v130
	v_fmamk_f32 v130, v133, 0x3e16c740, v153
	v_exp_f32_e32 v197, v130
	v_fmamk_f32 v130, v134, 0x3e16c740, v153
	v_exp_f32_e32 v134, v130
	v_fmamk_f32 v130, v135, 0x3e16c740, v153
	v_exp_f32_e32 v135, v130
	v_fmamk_f32 v130, v136, 0x3e16c740, v153
	v_exp_f32_e32 v136, v130
	v_fmamk_f32 v130, v137, 0x3e16c740, v153
	v_exp_f32_e32 v137, v130
	v_fmamk_f32 v130, v138, 0x3e16c740, v153
	v_exp_f32_e32 v138, v130
	v_fmamk_f32 v130, v139, 0x3e16c740, v153
	v_exp_f32_e32 v139, v130
	v_fmamk_f32 v130, v140, 0x3e16c740, v153
	v_exp_f32_e32 v140, v130
	v_fmamk_f32 v130, v141, 0x3e16c740, v153
	v_exp_f32_e32 v141, v130
	v_fmamk_f32 v130, v142, 0x3e16c740, v153
	v_exp_f32_e32 v142, v130
	v_fmamk_f32 v130, v143, 0x3e16c740, v153
	v_exp_f32_e32 v143, v130
	v_fmamk_f32 v130, v144, 0x3e16c740, v153
	v_fmac_f32_e32 v153, 0x3e16c740, v145
	v_exp_f32_e32 v144, v130
	v_exp_f32_e32 v145, v153
	v_add_f32_e32 v130, v160, v196
	v_add_f32_e32 v131, v161, v197
	v_add_f32_e32 v132, v134, v136
	v_add_f32_e32 v133, v135, v137
	v_add_f32_e32 v130, 0, v130
	v_add_f32_e32 v131, 0, v131
	v_cvt_pk_bf16_f32 v134, v134, v135
	v_add_f32_e32 v130, v132, v130
	v_add_f32_e32 v131, v133, v131
	v_add_f32_e32 v132, v138, v140
	v_add_f32_e32 v133, v139, v141
	v_cvt_pk_bf16_f32 v135, v136, v137
	v_add_f32_e32 v130, v132, v130
	v_add_f32_e32 v131, v133, v131
	v_add_f32_e32 v132, v142, v144
	v_add_f32_e32 v133, v143, v145
	v_cvt_pk_bf16_f32 v136, v138, v139
	v_add_f32_e32 v130, v132, v130
	v_add_f32_e32 v131, v133, v131
	v_cvt_pk_bf16_f32 v132, v160, v161
	v_add_f32_e32 v130, v130, v131
	v_mov_b32_e32 v131, v130
	v_cvt_pk_bf16_f32 v133, v196, v197
	v_add_f32_e32 v130, v182, v130
	v_add_f32_e32 v131, v183, v131
	v_cvt_pk_bf16_f32 v137, v140, v141
	s_waitcnt lgkmcnt(7)
	v_mfma_f32_16x16x32_bf16 v[54:57], v[110:113], v[132:135], v[54:57]
	v_max_f32_e32 v131, v127, v127
	v_cvt_pk_bf16_f32 v138, v142, v143
	v_cvt_pk_bf16_f32 v139, v144, v145
	s_waitcnt lgkmcnt(6)
	v_mfma_f32_16x16x32_bf16 v[50:53], v[106:109], v[132:135], v[50:53]
	s_waitcnt lgkmcnt(5)
	v_mfma_f32_16x16x32_bf16 v[46:49], v[102:105], v[132:135], v[46:49]
	s_waitcnt lgkmcnt(4)
	v_mfma_f32_16x16x32_bf16 v[42:45], v[98:101], v[132:135], v[42:45]
	v_max_f32_e32 v132, v126, v126
	v_max_f32_e32 v131, v132, v131
	v_max3_f32 v132, v129, v122, v123
	v_max3_f32 v133, v124, v125, v118
	v_max3_f32 v131, v131, v128, v132
	v_max3_f32 v132, v119, v120, v121
	v_max3_f32 v134, v114, v115, v116
	v_max3_f32 v131, v131, v133, v132
	s_waitcnt lgkmcnt(3)
	v_mfma_f32_16x16x32_bf16 v[54:57], v[94:97], v[136:139], v[54:57]
	v_max3_f32 v131, v131, v134, v117
	v_sub_f32_e32 v132, v131, v185
	v_mul_f32_e32 v132, 0x3e16c740, v132
	s_waitcnt lgkmcnt(2)
	v_mfma_f32_16x16x32_bf16 v[50:53], v[90:93], v[136:139], v[50:53]
	v_cmp_lt_f32_e32 vcc, s8, v132
	s_waitcnt lgkmcnt(1)
	v_mfma_f32_16x16x32_bf16 v[46:49], v[86:89], v[136:139], v[46:49]
	s_waitcnt lgkmcnt(0)
	v_mfma_f32_16x16x32_bf16 v[42:45], v[82:85], v[136:139], v[42:45]
	s_cbranch_vccz .LBB0_626
	v_mbcnt_hi_u32_b32 v132, -1, v203
	v_and_b32_e32 v134, 64, v132
	v_xor_b32_e32 v133, 16, v132
	v_add_u32_e32 v134, 64, v134
	v_cmp_lt_i32_e32 vcc, v133, v134
	s_nop 1
	v_cndmask_b32_e32 v133, v132, v133, vcc
	v_lshlrev_b32_e32 v133, 2, v133
	ds_bpermute_b32 v133, v133, v131
	v_max_f32_e32 v131, v131, v131
	s_waitcnt lgkmcnt(0)
	v_max_f32_e32 v133, v133, v133
	v_max_f32_e32 v131, v131, v133
	v_xor_b32_e32 v133, 32, v132
	v_cmp_lt_i32_e32 vcc, v133, v134
	s_nop 1
	v_cndmask_b32_e32 v132, v132, v133, vcc
	v_lshlrev_b32_e32 v132, 2, v132
	ds_bpermute_b32 v132, v132, v131
	s_waitcnt lgkmcnt(0)
	v_max3_f32 v131, v185, v131, v132
	v_sub_f32_e32 v132, v185, v131
	v_mul_f32_e32 v132, 0x3e16c740, v132
	v_exp_f32_e32 v132, v132
	v_mov_b32_e32 v185, v131
	v_mul_f32_e32 v183, v183, v132
	v_pk_mul_f32 v[28:29], v[28:29], v[132:133] op_sel_hi:[1,0]
	v_pk_mul_f32 v[26:27], v[26:27], v[132:133] op_sel_hi:[1,0]
	v_pk_mul_f32 v[32:33], v[32:33], v[132:133] op_sel_hi:[1,0]
	v_pk_mul_f32 v[30:31], v[30:31], v[132:133] op_sel_hi:[1,0]
	v_pk_mul_f32 v[36:37], v[36:37], v[132:133] op_sel_hi:[1,0]
	v_pk_mul_f32 v[34:35], v[34:35], v[132:133] op_sel_hi:[1,0]
	v_pk_mul_f32 v[40:41], v[40:41], v[132:133] op_sel_hi:[1,0]
	v_pk_mul_f32 v[38:39], v[38:39], v[132:133] op_sel_hi:[1,0]
.LBB0_626:
	v_mul_f32_e32 v137, 0xbe16c740, v185
	v_fmamk_f32 v122, v122, 0x3e16c740, v137
	v_exp_f32_e32 v132, v122
	v_fmamk_f32 v122, v123, 0x3e16c740, v137
	v_fmamk_f32 v126, v126, 0x3e16c740, v137
	v_fmamk_f32 v127, v127, 0x3e16c740, v137
	v_fmamk_f32 v128, v128, 0x3e16c740, v137
	v_fmamk_f32 v129, v129, 0x3e16c740, v137
	v_exp_f32_e32 v133, v122
	v_fmamk_f32 v122, v124, 0x3e16c740, v137
	v_exp_f32_e32 v126, v126
	v_exp_f32_e32 v127, v127
	v_exp_f32_e32 v128, v128
	v_exp_f32_e32 v129, v129
	v_exp_f32_e32 v124, v122
	v_fmamk_f32 v122, v125, 0x3e16c740, v137
	v_fmamk_f32 v114, v114, 0x3e16c740, v137
	v_exp_f32_e32 v125, v122
	v_fmamk_f32 v118, v118, 0x3e16c740, v137
	v_fmamk_f32 v119, v119, 0x3e16c740, v137
	v_fmamk_f32 v120, v120, 0x3e16c740, v137
	v_fmamk_f32 v121, v121, 0x3e16c740, v137
	v_exp_f32_e32 v134, v114
	v_fmamk_f32 v114, v115, 0x3e16c740, v137
	v_exp_f32_e32 v118, v118
	v_exp_f32_e32 v119, v119
	v_exp_f32_e32 v120, v120
	v_exp_f32_e32 v121, v121
	v_exp_f32_e32 v135, v114
	v_fmamk_f32 v114, v116, 0x3e16c740, v137
	v_fmac_f32_e32 v137, 0x3e16c740, v117
	v_exp_f32_e32 v136, v114
	v_exp_f32_e32 v137, v137
	v_add_f32_e32 v114, v126, v128
	v_add_f32_e32 v115, v127, v129
	v_add_f32_e32 v116, v132, v124
	v_add_f32_e32 v117, v133, v125
	v_add_f32_e32 v114, 0, v114
	v_add_f32_e32 v115, 0, v115
	v_mov_b32_e32 v131, v183
	v_add_f32_e32 v114, v116, v114
	v_add_f32_e32 v115, v117, v115
	v_add_f32_e32 v116, v118, v120
	v_add_f32_e32 v117, v119, v121
	v_cvt_pk_bf16_f32 v118, v118, v119
	v_add_f32_e32 v114, v116, v114
	v_add_f32_e32 v115, v117, v115
	v_add_f32_e32 v116, v134, v136
	v_add_f32_e32 v117, v135, v137
	v_cvt_pk_bf16_f32 v119, v120, v121
	v_add_f32_e32 v114, v116, v114
	v_add_f32_e32 v115, v117, v115
	v_cvt_pk_bf16_f32 v116, v132, v133
	v_add_f32_e32 v114, v114, v115
	v_add_f32_e32 v122, v130, v114
	v_add_f32_e32 v123, v131, v114
	v_cvt_pk_bf16_f32 v114, v126, v127
	v_cvt_pk_bf16_f32 v115, v128, v129
	v_cvt_pk_bf16_f32 v117, v124, v125
	v_cvt_pk_bf16_f32 v120, v134, v135
	v_cvt_pk_bf16_f32 v121, v136, v137
	v_mfma_f32_16x16x32_bf16 v[26:29], v[110:113], v[114:117], v[26:29]
	v_mov_b64_e32 v[160:161], v[184:185]
	v_lshl_add_u64 v[158:159], v[0:1], 1, v[158:159]
	s_cmp_lg_u32 s0, s13
	v_mfma_f32_16x16x32_bf16 v[30:33], v[106:109], v[114:117], v[30:33]
	s_barrier
	v_mfma_f32_16x16x32_bf16 v[34:37], v[102:105], v[114:117], v[34:37]
	v_mfma_f32_16x16x32_bf16 v[38:41], v[98:101], v[114:117], v[38:41]
	v_mfma_f32_16x16x32_bf16 v[26:29], v[94:97], v[118:121], v[26:29]
	v_mfma_f32_16x16x32_bf16 v[30:33], v[90:93], v[118:121], v[30:33]
	v_mfma_f32_16x16x32_bf16 v[34:37], v[86:89], v[118:121], v[34:37]
	v_mfma_f32_16x16x32_bf16 v[38:41], v[82:85], v[118:121], v[38:41]
	s_cbranch_scc0 .LBB0_628
	v_mov_b32_e32 v131, v123
	v_mov_b64_e32 v[182:183], v[130:131]
	s_mov_b32 s14, s13
	s_branch .LBB0_611

.LBB0_636:
	v_mul_f32_e32 v0, 0xbe16c740, v160
	v_fmamk_f32 v106, v106, 0x3e16c740, v0
	v_fmamk_f32 v107, v107, 0x3e16c740, v0
	v_fmamk_f32 v108, v108, 0x3e16c740, v0
	v_fmamk_f32 v109, v109, 0x3e16c740, v0
	v_exp_f32_e32 v106, v106
	v_exp_f32_e32 v107, v107
	v_exp_f32_e32 v108, v108
	v_exp_f32_e32 v109, v109
	v_fmamk_f32 v110, v110, 0x3e16c740, v0
	v_fmamk_f32 v111, v111, 0x3e16c740, v0
	v_fmamk_f32 v112, v112, 0x3e16c740, v0
	v_fmamk_f32 v113, v113, 0x3e16c740, v0
	v_exp_f32_e32 v110, v110
	v_exp_f32_e32 v111, v111
	v_exp_f32_e32 v112, v112
	v_exp_f32_e32 v113, v113
	v_fmamk_f32 v114, v114, 0x3e16c740, v0
	v_fmamk_f32 v115, v115, 0x3e16c740, v0
	v_fmamk_f32 v116, v116, 0x3e16c740, v0
	v_fmamk_f32 v117, v117, 0x3e16c740, v0
	v_exp_f32_e32 v114, v114
	v_exp_f32_e32 v115, v115
	v_exp_f32_e32 v116, v116
	v_exp_f32_e32 v117, v117
	v_mov_b32_e32 v131, v123
	v_fmamk_f32 v118, v118, 0x3e16c740, v0
	v_fmamk_f32 v119, v119, 0x3e16c740, v0
	v_fmamk_f32 v120, v120, 0x3e16c740, v0
	v_fmac_f32_e32 v0, 0x3e16c740, v121
	v_add_f32_e32 v122, v106, v108
	v_add_f32_e32 v123, v107, v109
	v_exp_f32_e32 v118, v118
	v_exp_f32_e32 v119, v119
	v_exp_f32_e32 v120, v120
	v_exp_f32_e32 v121, v0
	v_add_f32_e32 v122, 0, v122
	v_add_f32_e32 v123, 0, v123
	v_add_f32_e32 v126, v110, v112
	v_add_f32_e32 v127, v111, v113
	v_cvt_pk_bf16_f32 v106, v106, v107
	v_cvt_pk_bf16_f32 v107, v108, v109
	v_cvt_pk_bf16_f32 v108, v110, v111
	v_cvt_pk_bf16_f32 v109, v112, v113
	v_add_f32_e32 v122, v126, v122
	v_add_f32_e32 v123, v127, v123
	v_add_f32_e32 v126, v114, v116
	v_add_f32_e32 v127, v115, v117
	v_cvt_pk_bf16_f32 v110, v114, v115
	v_cvt_pk_bf16_f32 v111, v116, v117
	s_waitcnt lgkmcnt(5)
	v_mfma_f32_16x16x32_bf16 v[54:57], v[74:77], v[106:109], v[54:57]
	v_cvt_pk_bf16_f32 v112, v118, v119
	v_cvt_pk_bf16_f32 v113, v120, v121
	v_max_f32_e32 v0, v71, v71
	s_waitcnt lgkmcnt(2)
	v_mfma_f32_16x16x32_bf16 v[50:53], v[78:81], v[106:109], v[50:53]
	v_add_f32_e64 v122, v126, v122
	v_add_f32_e64 v123, v127, v123
	v_add_f32_e32 v126, v118, v120
	v_add_f32_e32 v127, v119, v121
	v_mfma_f32_16x16x32_bf16 v[114:117], v[82:85], v[106:109], v[46:49]
	v_add_f32_e64 v122, v126, v122
	v_add_f32_e64 v123, v127, v123
	v_add_f32_e32 v122, v122, v123
	v_mov_b32_e32 v123, v122
	v_mfma_f32_16x16x32_bf16 v[106:109], v[86:89], v[106:109], v[42:45]
	v_add_f32_e64 v126, v130, v122
	v_add_f32_e64 v127, v131, v123
	s_waitcnt lgkmcnt(1)
	v_mfma_f32_16x16x32_bf16 v[42:45], v[90:93], v[110:113], v[54:57]
	s_waitcnt lgkmcnt(0)
	v_mfma_f32_16x16x32_bf16 v[54:57], v[102:105], v[110:113], v[106:109]
	s_nop 2
	v_max_f32_e32 v106, v70, v70
	v_max_f32_e32 v0, v106, v0
	v_max3_f32 v106, v73, v66, v67
	v_max3_f32 v107, v68, v69, v62
	v_max3_f32 v0, v0, v72, v106
	v_max3_f32 v106, v63, v64, v65
	v_max3_f32 v108, v58, v59, v60
	v_max3_f32 v0, v0, v107, v106
	v_mfma_f32_16x16x32_bf16 v[46:49], v[94:97], v[110:113], v[50:53]
	v_max3_f32 v0, v0, v108, v61
	v_sub_f32_e32 v106, v0, v125
	v_mul_f32_e32 v106, 0x3e16c740, v106
	v_mfma_f32_16x16x32_bf16 v[50:53], v[98:101], v[110:113], v[114:117]
	v_cmp_lt_f32_e32 vcc, s0, v106
	s_cbranch_vccz .LBB0_638
	v_mbcnt_hi_u32_b32 v106, -1, v203
	v_and_b32_e32 v108, 64, v106
	v_xor_b32_e32 v107, 16, v106
	v_add_u32_e32 v108, 64, v108
	v_cmp_lt_i32_e32 vcc, v107, v108
	s_nop 1
	v_cndmask_b32_e32 v107, v106, v107, vcc
	v_lshlrev_b32_e32 v107, 2, v107
	ds_bpermute_b32 v107, v107, v0
	v_max_f32_e32 v0, v0, v0
	s_waitcnt lgkmcnt(0)
	v_max_f32_e32 v107, v107, v107
	v_max_f32_e32 v0, v0, v107
	v_xor_b32_e32 v107, 32, v106
	v_cmp_lt_i32_e32 vcc, v107, v108
	s_nop 1
	v_cndmask_b32_e32 v106, v106, v107, vcc
	v_lshlrev_b32_e32 v106, 2, v106
	ds_bpermute_b32 v106, v106, v0
	s_waitcnt lgkmcnt(0)
	v_max3_f32 v106, v125, v0, v106
	v_sub_f32_e32 v0, v125, v106
	v_mul_f32_e32 v0, 0x3e16c740, v0
	v_exp_f32_e32 v0, v0
	v_mov_b32_e32 v125, v106
	v_mul_f32_e32 v131, v131, v0
	v_pk_mul_f32 v[28:29], v[28:29], v[0:1] op_sel_hi:[1,0]
	v_pk_mul_f32 v[26:27], v[26:27], v[0:1] op_sel_hi:[1,0]
	v_pk_mul_f32 v[32:33], v[32:33], v[0:1] op_sel_hi:[1,0]
	v_pk_mul_f32 v[30:31], v[30:31], v[0:1] op_sel_hi:[1,0]
	v_pk_mul_f32 v[36:37], v[36:37], v[0:1] op_sel_hi:[1,0]
	v_pk_mul_f32 v[34:35], v[34:35], v[0:1] op_sel_hi:[1,0]
	v_pk_mul_f32 v[40:41], v[40:41], v[0:1] op_sel_hi:[1,0]
	v_pk_mul_f32 v[38:39], v[38:39], v[0:1] op_sel_hi:[1,0]
.LBB0_638:
	v_mul_f32_e32 v0, 0xbe16c740, v125
	v_fmamk_f32 v70, v70, 0x3e16c740, v0
	v_fmamk_f32 v71, v71, 0x3e16c740, v0
	v_fmamk_f32 v72, v72, 0x3e16c740, v0
	v_fmamk_f32 v73, v73, 0x3e16c740, v0
	v_exp_f32_e32 v70, v70
	v_exp_f32_e32 v71, v71
	v_exp_f32_e32 v72, v72
	v_exp_f32_e32 v73, v73
	v_fmamk_f32 v66, v66, 0x3e16c740, v0
	v_fmamk_f32 v67, v67, 0x3e16c740, v0
	v_fmamk_f32 v68, v68, 0x3e16c740, v0
	v_fmamk_f32 v69, v69, 0x3e16c740, v0
	v_fmamk_f32 v62, v62, 0x3e16c740, v0
	v_fmamk_f32 v63, v63, 0x3e16c740, v0
	v_fmamk_f32 v64, v64, 0x3e16c740, v0
	v_fmamk_f32 v65, v65, 0x3e16c740, v0
	v_fmamk_f32 v58, v58, 0x3e16c740, v0
	v_exp_f32_e32 v66, v66
	v_exp_f32_e32 v67, v67
	v_exp_f32_e32 v68, v68
	v_exp_f32_e32 v69, v69
	v_exp_f32_e32 v62, v62
	v_exp_f32_e32 v63, v63
	v_exp_f32_e32 v64, v64
	v_exp_f32_e32 v65, v65
	v_exp_f32_e32 v106, v58
	v_fmamk_f32 v58, v59, 0x3e16c740, v0
	v_exp_f32_e32 v107, v58
	v_fmamk_f32 v58, v60, 0x3e16c740, v0
	v_fmac_f32_e32 v0, 0x3e16c740, v61
	v_exp_f32_e32 v108, v58
	v_exp_f32_e32 v109, v0
	v_add_f32_e32 v58, v70, v72
	v_add_f32_e32 v59, v71, v73
	v_add_f32_e32 v60, v66, v68
	v_add_f32_e32 v61, v67, v69
	v_add_f32_e32 v58, 0, v58
	v_add_f32_e32 v59, 0, v59
	v_mov_b32_e32 v127, v131
	v_add_f32_e32 v58, v60, v58
	v_add_f32_e32 v59, v61, v59
	v_add_f32_e32 v60, v62, v64
	v_add_f32_e32 v61, v63, v65
	v_mov_b64_e32 v[122:123], v[124:125]
	v_add_f32_e32 v58, v60, v58
	v_add_f32_e32 v59, v61, v59
	v_add_f32_e32 v60, v106, v108
	v_add_f32_e32 v61, v107, v109
	s_nop 0
	v_add_f32_e32 v58, v60, v58
	v_add_f32_e32 v59, v61, v59
	v_cvt_pk_bf16_f32 v60, v66, v67
	v_add_f32_e32 v0, v58, v59
	v_add_f32_e32 v124, v126, v0
	v_add_f32_e32 v125, v127, v0
	v_cvt_pk_bf16_f32 v58, v70, v71
	v_cvt_pk_bf16_f32 v59, v72, v73
	v_cvt_pk_bf16_f32 v61, v68, v69
	v_add_u32_e32 v0, 0, v150
	s_barrier
	v_mfma_f32_16x16x32_bf16 v[26:29], v[74:77], v[58:61], v[26:29]
	v_cvt_pk_bf16_f32 v62, v62, v63
	v_cvt_pk_bf16_f32 v63, v64, v65
	v_mfma_f32_16x16x32_bf16 v[30:33], v[78:81], v[58:61], v[30:33]
	v_cvt_pk_bf16_f32 v64, v106, v107
	v_cvt_pk_bf16_f32 v65, v108, v109
	v_mfma_f32_16x16x32_bf16 v[34:37], v[82:85], v[58:61], v[34:37]
	v_add_u32_e32 v82, v0, v187
	ds_read_b128 v[114:117], v82 offset:22528
	ds_read_b128 v[118:121], v82 offset:22592
	v_mfma_f32_16x16x32_bf16 v[38:41], v[86:89], v[58:61], v[38:41]
	ds_read_b128 v[66:69], v82 offset:25856
	ds_read_b128 v[74:77], v82 offset:22656
	ds_read_b128 v[58:61], v82 offset:32512
	v_mfma_f32_16x16x32_bf16 v[26:29], v[90:93], v[62:65], v[26:29]
	ds_read_b128 v[78:81], v82 offset:25920
	ds_read_b128 v[70:73], v82 offset:29248
	ds_read_b128 v[110:113], v82 offset:25984
	v_mfma_f32_16x16x32_bf16 v[30:33], v[94:97], v[62:65], v[30:33]
	ds_read_b128 v[106:109], v82 offset:29312
	v_add_u32_e32 v0, v0, v151
	v_mfma_f32_16x16x32_bf16 v[34:37], v[98:101], v[62:65], v[34:37]
	ds_read_b128 v[98:101], v82 offset:32576
	v_mfma_f32_16x16x32_bf16 v[38:41], v[102:105], v[62:65], v[38:41]
	ds_read_b128 v[62:65], v82 offset:29184
	ds_read_b128 v[102:105], v82 offset:32640
	s_waitcnt lgkmcnt(11)
	v_mfma_f32_16x16x32_bf16 v[82:85], v[114:117], v[22:25], 0
	s_waitcnt lgkmcnt(10)
	v_mfma_f32_16x16x32_bf16 v[82:85], v[118:121], v[18:21], v[82:85]
	s_waitcnt lgkmcnt(8)
	v_mfma_f32_16x16x32_bf16 v[82:85], v[74:77], v[14:17], v[82:85]
	v_mfma_f32_16x16x32_bf16 v[86:89], v[66:69], v[22:25], 0
	s_waitcnt lgkmcnt(6)
	v_mfma_f32_16x16x32_bf16 v[86:89], v[78:81], v[18:21], v[86:89]
	s_waitcnt lgkmcnt(4)
	v_mfma_f32_16x16x32_bf16 v[86:89], v[110:113], v[14:17], v[86:89]
	s_waitcnt lgkmcnt(1)
	v_mfma_f32_16x16x32_bf16 v[90:93], v[62:65], v[22:25], 0
	v_mfma_f32_16x16x32_bf16 v[90:93], v[70:73], v[18:21], v[90:93]
	v_mfma_f32_16x16x32_bf16 v[90:93], v[106:109], v[14:17], v[90:93]
	v_mfma_f32_16x16x32_bf16 v[22:25], v[58:61], v[22:25], 0
	v_mfma_f32_16x16x32_bf16 v[18:21], v[98:101], v[18:21], v[22:25]
	s_waitcnt lgkmcnt(0)
	v_mfma_f32_16x16x32_bf16 v[94:97], v[102:105], v[14:17], v[18:21]
	s_nop 4
	ds_read_b128 v[22:25], v0 offset:40448
	v_mfma_f32_16x16x32_bf16 v[14:17], v[114:117], v[2:5], 0
	ds_read_b128 v[18:21], v0 offset:42752
	v_mfma_f32_16x16x32_bf16 v[14:17], v[118:121], v[6:9], v[14:17]
	v_mfma_f32_16x16x32_bf16 v[74:77], v[74:77], v[10:13], v[14:17]
	v_mfma_f32_16x16x32_bf16 v[14:17], v[66:69], v[2:5], 0
	v_mfma_f32_16x16x32_bf16 v[14:17], v[78:81], v[6:9], v[14:17]
	v_mfma_f32_16x16x32_bf16 v[78:81], v[110:113], v[10:13], v[14:17]
	v_mfma_f32_16x16x32_bf16 v[14:17], v[62:65], v[2:5], 0
	ds_read_b128 v[62:65], v0 offset:35840
	v_mfma_f32_16x16x32_bf16 v[14:17], v[70:73], v[6:9], v[14:17]
	v_mfma_f32_16x16x32_bf16 v[70:73], v[106:109], v[10:13], v[14:17]
	v_mfma_f32_16x16x32_bf16 v[2:5], v[58:61], v[2:5], 0
	ds_read_b128 v[58:61], v0 offset:38144
	s_nop 4
	ds_read_b128 v[14:17], v0 offset:35904
	v_mfma_f32_16x16x32_bf16 v[2:5], v[98:101], v[6:9], v[2:5]
	ds_read_b128 v[6:9], v0 offset:40512
	v_max_f32_e32 v98, v82, v82
	v_max3_f32 v99, v88, v89, v90
	v_mfma_f32_16x16x32_bf16 v[66:69], v[102:105], v[10:13], v[2:5]
	ds_read_b128 v[10:13], v0 offset:42816
	v_max3_f32 v100, v94, v95, v96
	s_nop 1
	ds_read_b128 v[2:5], v0 offset:38208
	v_max_f32_e32 v0, v83, v83
	v_max_f32_e32 v0, v98, v0
	v_max3_f32 v98, v85, v86, v87
	v_max3_f32 v0, v0, v84, v98
	v_max3_f32 v98, v91, v92, v93
	v_max3_f32 v0, v0, v99, v98
	v_max3_f32 v0, v0, v100, v97
	v_sub_f32_e32 v98, v0, v122
	v_mul_f32_e32 v98, 0x3e16c740, v98
	v_cmp_lt_f32_e32 vcc, s0, v98
	s_cbranch_vccz .LBB0_640
	v_mbcnt_hi_u32_b32 v98, -1, v203
	v_and_b32_e32 v100, 64, v98
	v_xor_b32_e32 v99, 16, v98
	v_add_u32_e32 v100, 64, v100
	v_cmp_lt_i32_e32 vcc, v99, v100
	s_nop 1
	v_cndmask_b32_e32 v99, v98, v99, vcc
	v_lshlrev_b32_e32 v99, 2, v99
	ds_bpermute_b32 v99, v99, v0
	v_max_f32_e32 v0, v0, v0
	s_waitcnt lgkmcnt(0)
	v_max_f32_e32 v99, v99, v99
	v_max_f32_e32 v0, v0, v99
	v_xor_b32_e32 v99, 32, v98
	v_cmp_lt_i32_e32 vcc, v99, v100
	s_nop 1
	v_cndmask_b32_e32 v98, v98, v99, vcc
	v_lshlrev_b32_e32 v98, 2, v98
	ds_bpermute_b32 v98, v98, v0
	s_waitcnt lgkmcnt(0)
	v_max3_f32 v98, v122, v0, v98
	v_sub_f32_e32 v0, v122, v98
	v_mul_f32_e32 v0, 0x3e16c740, v0
	v_exp_f32_e32 v0, v0
	v_mov_b32_e32 v122, v98
	v_mul_f32_e32 v124, v126, v0
	v_pk_mul_f32 v[44:45], v[44:45], v[0:1] op_sel_hi:[1,0]
	v_pk_mul_f32 v[42:43], v[42:43], v[0:1] op_sel_hi:[1,0]
	v_pk_mul_f32 v[48:49], v[48:49], v[0:1] op_sel_hi:[1,0]
	v_pk_mul_f32 v[46:47], v[46:47], v[0:1] op_sel_hi:[1,0]
	v_pk_mul_f32 v[52:53], v[52:53], v[0:1] op_sel_hi:[1,0]
	v_pk_mul_f32 v[50:51], v[50:51], v[0:1] op_sel_hi:[1,0]
	v_pk_mul_f32 v[56:57], v[56:57], v[0:1] op_sel_hi:[1,0]
	v_pk_mul_f32 v[54:55], v[54:55], v[0:1] op_sel_hi:[1,0]
	s_branch .LBB0_641

.LBB0_641:
	v_mul_f32_e32 v0, 0xbe16c740, v122
	v_fmamk_f32 v82, v82, 0x3e16c740, v0
	v_fmamk_f32 v83, v83, 0x3e16c740, v0
	v_fmamk_f32 v84, v84, 0x3e16c740, v0
	v_fmamk_f32 v85, v85, 0x3e16c740, v0
	v_fmamk_f32 v86, v86, 0x3e16c740, v0
	v_fmamk_f32 v87, v87, 0x3e16c740, v0
	v_fmamk_f32 v88, v88, 0x3e16c740, v0
	v_fmamk_f32 v89, v89, 0x3e16c740, v0
	v_exp_f32_e32 v82, v82
	v_exp_f32_e32 v83, v83
	v_exp_f32_e32 v84, v84
	v_exp_f32_e32 v85, v85
	v_exp_f32_e32 v86, v86
	v_exp_f32_e32 v87, v87
	v_exp_f32_e32 v88, v88
	v_exp_f32_e32 v89, v89
	v_fmamk_f32 v90, v90, 0x3e16c740, v0
	v_fmamk_f32 v91, v91, 0x3e16c740, v0
	v_fmamk_f32 v92, v92, 0x3e16c740, v0
	v_fmamk_f32 v93, v93, 0x3e16c740, v0
	v_fmamk_f32 v94, v94, 0x3e16c740, v0
	v_fmamk_f32 v95, v95, 0x3e16c740, v0
	v_fmamk_f32 v96, v96, 0x3e16c740, v0
	v_fmac_f32_e32 v0, 0x3e16c740, v97
	v_exp_f32_e32 v90, v90
	v_exp_f32_e32 v91, v91
	v_exp_f32_e32 v92, v92
	v_exp_f32_e32 v93, v93
	v_exp_f32_e32 v94, v94
	v_exp_f32_e32 v95, v95
	v_exp_f32_e32 v96, v96
	v_exp_f32_e32 v97, v0
	v_add_f32_e32 v98, v82, v84
	v_add_f32_e32 v99, v83, v85
	v_cvt_pk_bf16_f32 v82, v82, v83
	v_cvt_pk_bf16_f32 v83, v84, v85
	v_cvt_pk_bf16_f32 v84, v86, v87
	v_cvt_pk_bf16_f32 v85, v88, v89
	v_max_f32_e32 v0, v75, v75
	v_add_f32_e32 v98, 0, v98
	v_add_f32_e32 v99, 0, v99
	s_waitcnt lgkmcnt(5)
	v_mfma_f32_16x16x32_bf16 v[42:45], v[62:65], v[82:85], v[42:45]
	v_add_f32_e64 v100, v86, v88
	v_add_f32_e64 v101, v87, v89
	v_cvt_pk_bf16_f32 v86, v90, v91
	v_add_f32_e32 v98, v100, v98
	v_add_f32_e32 v99, v101, v99
	s_waitcnt lgkmcnt(4)
	v_mfma_f32_16x16x32_bf16 v[46:49], v[58:61], v[82:85], v[46:49]
	v_add_f32_e64 v100, v90, v92
	v_add_f32_e64 v101, v91, v93
	v_cvt_pk_bf16_f32 v87, v92, v93
	v_cvt_pk_bf16_f32 v88, v94, v95
	v_mfma_f32_16x16x32_bf16 v[50:53], v[22:25], v[82:85], v[50:53]
	v_cvt_pk_bf16_f32 v89, v96, v97
	v_add_f32_e32 v98, v100, v98
	v_add_f32_e32 v99, v101, v99
	v_add_f32_e32 v100, v94, v96
	v_add_f32_e32 v101, v95, v97
	v_mfma_f32_16x16x32_bf16 v[54:57], v[18:21], v[82:85], v[54:57]
	v_max_f32_e32 v82, v74, v74
	v_max_f32_e32 v0, v82, v0
	v_max3_f32 v82, v77, v78, v79
	v_max3_f32 v83, v80, v81, v70
	v_max3_f32 v0, v0, v76, v82
	v_max3_f32 v82, v71, v72, v73
	v_max3_f32 v84, v66, v67, v68
	v_max3_f32 v0, v0, v83, v82
	s_waitcnt lgkmcnt(3)
	v_mfma_f32_16x16x32_bf16 v[42:45], v[14:17], v[86:89], v[42:45]
	v_max3_f32 v82, v0, v84, v69
	v_add_f32_e32 v98, v100, v98
	v_add_f32_e32 v99, v101, v99
	v_sub_f32_e32 v0, v82, v123
	s_waitcnt lgkmcnt(0)
	v_mfma_f32_16x16x32_bf16 v[46:49], v[2:5], v[86:89], v[46:49]
	v_add_f32_e32 v98, v98, v99
	v_mov_b32_e32 v99, v98
	v_mul_f32_e32 v0, 0x3e16c740, v0
	v_add_f32_e32 v98, v124, v98
	v_add_f32_e32 v99, v125, v99
	v_mfma_f32_16x16x32_bf16 v[50:53], v[6:9], v[86:89], v[50:53]
	v_cmp_lt_f32_e32 vcc, s0, v0
	v_mfma_f32_16x16x32_bf16 v[54:57], v[10:13], v[86:89], v[54:57]
	s_cbranch_vccz .LBB0_702
	v_mbcnt_hi_u32_b32 v0, -1, v203
	v_and_b32_e32 v83, 64, v0
	v_xor_b32_e32 v100, 16, v0
	v_add_u32_e32 v99, 64, v83
	v_cmp_lt_i32_e32 vcc, v100, v99
	v_xor_b32_e32 v101, 32, v0
	s_nop 0
	v_cndmask_b32_e32 v83, v0, v100, vcc
	v_lshlrev_b32_e32 v83, 2, v83
	ds_bpermute_b32 v83, v83, v82
	v_max_f32_e32 v82, v82, v82
	v_cmp_lt_i32_e32 vcc, v101, v99
	s_waitcnt lgkmcnt(0)
	v_max_f32_e32 v83, v83, v83
	v_max_f32_e32 v82, v82, v83
	v_cndmask_b32_e32 v83, v0, v101, vcc
	v_lshlrev_b32_e32 v83, 2, v83
	ds_bpermute_b32 v83, v83, v82
	s_waitcnt lgkmcnt(0)
	v_max3_f32 v103, v123, v82, v83
	v_sub_f32_e32 v82, v123, v103
	v_mul_f32_e32 v82, 0x3e16c740, v82
	v_exp_f32_e32 v82, v82
	s_nop 0
	v_mul_f32_e32 v102, v125, v82
	v_pk_mul_f32 v[96:97], v[28:29], v[82:83] op_sel_hi:[1,0]
	v_pk_mul_f32 v[94:95], v[26:27], v[82:83] op_sel_hi:[1,0]
	v_pk_mul_f32 v[92:93], v[32:33], v[82:83] op_sel_hi:[1,0]
	v_pk_mul_f32 v[90:91], v[30:31], v[82:83] op_sel_hi:[1,0]
	v_pk_mul_f32 v[88:89], v[36:37], v[82:83] op_sel_hi:[1,0]
	v_pk_mul_f32 v[86:87], v[34:35], v[82:83] op_sel_hi:[1,0]
	v_pk_mul_f32 v[84:85], v[40:41], v[82:83] op_sel_hi:[1,0]
	v_pk_mul_f32 v[82:83], v[38:39], v[82:83] op_sel_hi:[1,0]
	s_cbranch_execnz .LBB0_644

.LBB0_644:
	v_mul_f32_e32 v41, 0xbe16c740, v103
	v_fmamk_f32 v26, v74, 0x3e16c740, v41
	v_fmamk_f32 v27, v75, 0x3e16c740, v41
	v_fmamk_f32 v28, v76, 0x3e16c740, v41
	v_fmamk_f32 v29, v77, 0x3e16c740, v41
	v_exp_f32_e32 v26, v26
	v_exp_f32_e32 v27, v27
	v_exp_f32_e32 v28, v28
	v_exp_f32_e32 v29, v29
	v_fmamk_f32 v30, v78, 0x3e16c740, v41
	v_fmamk_f32 v31, v79, 0x3e16c740, v41
	v_fmamk_f32 v32, v80, 0x3e16c740, v41
	v_fmamk_f32 v33, v81, 0x3e16c740, v41
	v_exp_f32_e32 v30, v30
	v_exp_f32_e32 v31, v31
	v_exp_f32_e32 v32, v32
	v_exp_f32_e32 v33, v33
	v_fmamk_f32 v34, v70, 0x3e16c740, v41
	v_fmamk_f32 v35, v71, 0x3e16c740, v41
	v_fmamk_f32 v36, v72, 0x3e16c740, v41
	v_fmamk_f32 v37, v73, 0x3e16c740, v41
	v_exp_f32_e32 v34, v34
	v_exp_f32_e32 v35, v35
	v_exp_f32_e32 v36, v36
	v_exp_f32_e32 v37, v37
	v_fmamk_f32 v38, v66, 0x3e16c740, v41
	v_fmamk_f32 v39, v67, 0x3e16c740, v41
	v_fmamk_f32 v40, v68, 0x3e16c740, v41
	v_fmac_f32_e32 v41, 0x3e16c740, v69
	v_exp_f32_e32 v38, v38
	v_exp_f32_e32 v39, v39
	v_exp_f32_e32 v40, v40
	v_exp_f32_e32 v41, v41
	v_add_f32_e32 v66, v26, v28
	v_add_f32_e32 v67, v27, v29
	v_add_f32_e32 v68, v30, v32
	v_add_f32_e32 v69, v31, v33
	v_add_f32_e32 v66, 0, v66
	v_add_f32_e32 v67, 0, v67
	v_cvt_pk_bf16_f32 v26, v26, v27
	v_add_f32_e32 v66, v68, v66
	v_add_f32_e32 v67, v69, v67
	v_add_f32_e32 v68, v34, v36
	v_add_f32_e32 v69, v35, v37
	v_cvt_pk_bf16_f32 v27, v28, v29
	v_cvt_pk_bf16_f32 v28, v30, v31
	v_cvt_pk_bf16_f32 v29, v32, v33
	v_add_f32_e32 v66, v68, v66
	v_add_f32_e32 v67, v69, v67
	v_add_f32_e32 v68, v38, v40
	v_add_f32_e32 v69, v39, v41
	v_cvt_pk_bf16_f32 v30, v34, v35
	v_cvt_pk_bf16_f32 v31, v36, v37
	v_cvt_pk_bf16_f32 v32, v38, v39
	v_cvt_pk_bf16_f32 v33, v40, v41
	v_mfma_f32_16x16x32_bf16 v[34:37], v[62:65], v[26:29], v[94:97]
	v_cmp_lt_i32_e32 vcc, v100, v99
	s_lshl_b64 s[0:1], s[10:11], 11
	v_readlane_b32 s4, v254, 33
	v_mfma_f32_16x16x32_bf16 v[38:41], v[58:61], v[26:29], v[90:93]
	v_readlane_b32 s5, v254, 34
	s_add_u32 s0, s4, s0
	s_addc_u32 s1, s5, s1
	v_mfma_f32_16x16x32_bf16 v[22:25], v[22:25], v[26:29], v[86:89]
	s_add_u32 s4, s0, s12
	s_addc_u32 s5, s1, 0
	v_mfma_f32_16x16x32_bf16 v[26:29], v[18:21], v[26:29], v[82:85]
	s_barrier
	v_add_f32_e32 v66, v68, v66
	v_add_f32_e32 v67, v69, v67
	v_mfma_f32_16x16x32_bf16 v[18:21], v[2:5], v[30:33], v[38:41]
	v_add_f32_e32 v66, v66, v67
	v_add_f32_e32 v66, v102, v66
	v_mfma_f32_16x16x32_bf16 v[2:5], v[10:13], v[30:33], v[26:29]
	v_cndmask_b32_e32 v10, v0, v100, vcc
	v_cmp_lt_i32_e32 vcc, v101, v99
	s_nop 0
	v_lshlrev_b32_e32 v26, 2, v10
	v_cndmask_b32_e32 v0, v0, v101, vcc
	v_lshlrev_b32_e32 v27, 2, v0
	ds_bpermute_b32 v0, v26, v98
	v_mfma_f32_16x16x32_bf16 v[6:9], v[6:9], v[30:33], v[22:25]
	s_waitcnt lgkmcnt(0)
	v_add_f32_e32 v0, v98, v0
	ds_bpermute_b32 v10, v27, v0
	v_mfma_f32_16x16x32_bf16 v[14:17], v[14:17], v[30:33], v[34:37]
	s_waitcnt lgkmcnt(0)
	v_add_f32_e32 v0, v0, v10
	v_div_scale_f32 v10, s[0:1], v0, v0, 1.0
	v_rcp_f32_e32 v11, v10
	s_nop 0
	v_fma_f32 v12, -v10, v11, 1.0
	v_fmac_f32_e32 v11, v12, v11
	v_div_scale_f32 v12, vcc, 1.0, v0, 1.0
	v_mul_f32_e32 v13, v12, v11
	v_fma_f32 v22, -v10, v13, v12
	v_fmac_f32_e32 v13, v22, v11
	v_fma_f32 v10, -v10, v13, v12
	v_div_fmas_f32 v10, v10, v11, v13
	v_div_fixup_f32 v10, v10, v0, 1.0
	v_lshlrev_b64 v[12:13], 11, v[148:149]
	v_lshl_add_u64 v[12:13], s[4:5], 0, v[12:13]
	v_lshlrev_b32_e32 v0, 3, v186
	v_pk_mul_f32 v[22:23], v[44:45], v[10:11] op_sel_hi:[1,0]
	v_pk_mul_f32 v[24:25], v[42:43], v[10:11] op_sel_hi:[1,0]
	v_lshl_add_u64 v[12:13], v[12:13], 0, v[0:1]
	v_cvt_pk_bf16_f32 v24, v24, v25
	v_cvt_pk_bf16_f32 v25, v22, v23
	global_store_dwordx2 v[12:13], v[24:25], off
	v_pk_mul_f32 v[22:23], v[48:49], v[10:11] op_sel_hi:[1,0]
	v_pk_mul_f32 v[24:25], v[46:47], v[10:11] op_sel_hi:[1,0]
	s_nop 0
	v_cvt_pk_bf16_f32 v24, v24, v25
	v_cvt_pk_bf16_f32 v25, v22, v23
	global_store_dwordx2 v[12:13], v[24:25], off offset:32
	v_pk_mul_f32 v[22:23], v[52:53], v[10:11] op_sel_hi:[1,0]
	v_pk_mul_f32 v[24:25], v[50:51], v[10:11] op_sel_hi:[1,0]
	s_nop 0
	v_cvt_pk_bf16_f32 v24, v24, v25
	v_cvt_pk_bf16_f32 v25, v22, v23
	v_pk_mul_f32 v[22:23], v[56:57], v[10:11] op_sel_hi:[1,0]
	v_pk_mul_f32 v[10:11], v[54:55], v[10:11] op_sel_hi:[1,0]
	global_store_dwordx2 v[12:13], v[24:25], off offset:64
	v_cvt_pk_bf16_f32 v10, v10, v11
	v_cvt_pk_bf16_f32 v11, v22, v23
	global_store_dwordx2 v[12:13], v[10:11], off offset:96
	ds_bpermute_b32 v10, v26, v66
	s_waitcnt lgkmcnt(0)
	v_add_f32_e32 v10, v66, v10
	ds_bpermute_b32 v11, v27, v10
	s_waitcnt lgkmcnt(0)
	v_add_f32_e32 v10, v10, v11
	v_div_scale_f32 v11, s[0:1], v10, v10, 1.0
	v_rcp_f32_e32 v12, v11
	s_nop 0
	v_fma_f32 v13, -v11, v12, 1.0
	v_fmac_f32_e32 v12, v13, v12
	v_div_scale_f32 v13, vcc, 1.0, v10, 1.0
	v_mul_f32_e32 v22, v13, v12
	v_fma_f32 v23, -v11, v22, v13
	v_fmac_f32_e32 v22, v23, v12
	v_fma_f32 v11, -v11, v22, v13
	v_div_fmas_f32 v11, v11, v12, v22
	v_div_fixup_f32 v10, v11, v10, 1.0
	v_lshlrev_b64 v[12:13], 11, v[146:147]
	v_lshl_add_u64 v[12:13], s[4:5], 0, v[12:13]
	v_pk_mul_f32 v[16:17], v[16:17], v[10:11] op_sel_hi:[1,0]
	v_pk_mul_f32 v[14:15], v[14:15], v[10:11] op_sel_hi:[1,0]
	v_lshl_add_u64 v[12:13], v[12:13], 0, v[0:1]
	v_cvt_pk_bf16_f32 v14, v14, v15
	v_cvt_pk_bf16_f32 v15, v16, v17
	global_store_dwordx2 v[12:13], v[14:15], off
	v_pk_mul_f32 v[14:15], v[20:21], v[10:11] op_sel_hi:[1,0]
	v_pk_mul_f32 v[16:17], v[18:19], v[10:11] op_sel_hi:[1,0]
	v_pk_mul_f32 v[8:9], v[8:9], v[10:11] op_sel_hi:[1,0]
	v_pk_mul_f32 v[6:7], v[6:7], v[10:11] op_sel_hi:[1,0]
	v_pk_mul_f32 v[4:5], v[4:5], v[10:11] op_sel_hi:[1,0]
	v_pk_mul_f32 v[2:3], v[2:3], v[10:11] op_sel_hi:[1,0]
	v_cvt_pk_bf16_f32 v16, v16, v17
	v_cvt_pk_bf16_f32 v17, v14, v15
	v_cvt_pk_bf16_f32 v6, v6, v7
	v_cvt_pk_bf16_f32 v7, v8, v9
	v_cvt_pk_bf16_f32 v2, v2, v3
	v_cvt_pk_bf16_f32 v3, v4, v5
	global_store_dwordx2 v[12:13], v[16:17], off offset:32
	global_store_dwordx2 v[12:13], v[6:7], off offset:64
	global_store_dwordx2 v[12:13], v[2:3], off offset:96
